# SB work item prologue: second K/V tile pair fetched together with the first (free VGPRs for addresses), one exposed load latency instead of two
# baseline (speedup 1.0000x reference)
; DI int otid() { int t = threadIdx.x; asm volatile("" : "+v"(t)); return t; }
; DI void sb_item(const bf16_t* __restrict__ P, const bf16_t* __restrict__ VT, bf16_t* __restrict__ Y, int item, char* lds) {
;   const int tid = otid(), lane = tid & 63, wave = tid >> 6, l32 = lane & 31, hh = lane >> 5;
;   const int qb = item & 15, bh = item >> 4, b = bh >> 4, hd = bh & 15;
;   const int q0 = qb * 256 + wave * 32, qpos = q0 + l32;
;   const size_t tokbase = (size_t)b * SEQ;
;   bf16_t* Ks = (bf16_t*)lds;
;   bf16_t* VTs = Ks + 64 * LDT;
;   bf16x8 qf[4];
;   {
;     const bf16_t* qp = P + (tokbase + qpos) * LDP_O + hd * 64 + hh * 8;
; #pragma unroll
;     for (int s = 0; s < 4; ++s) qf[s] = *(const bf16x8*)(qp + s * 16);
;   }
;   f32x16 O[2], S[2];
; #pragma unroll
;   for (int dt = 0; dt < 2; ++dt)
; #pragma unroll
;     for (int e = 0; e < 16; ++e) O[dt][e] = 0.f;
;   float carry = 1.f;
;   const bf16_t* kb0 = P + tokbase * LDP_O + 1024 + hd * 64;
;   const bf16_t* vb0 = VT + (size_t)bh * 64 * SEQ;
;   const int kbs = 4 * qb + 3;
;   constexpr int TS = 64 * LDT;
;   u32x4 pfk = tile_fetch(kb0 + (size_t)kbs * 64 * LDP_O, LDP_O), pfv = tile_fetch(vb0 + kbs * 64, SEQ);
;   u32x4 pfk1 = tile_fetch(kb0 + (size_t)(kbs - 1) * 64 * LDP_O, LDP_O), pfv1 = tile_fetch(vb0 + (kbs - 1) * 64, SEQ);
;   __syncthreads();
;   tile_commit(Ks, pfk); tile_commit(Ks + TS, pfv); tile_commit(Ks + 2 * TS, pfk1); tile_commit(Ks + 3 * TS, pfv1);
;   if (kbs >= 3) {
;     pfk = tile_fetch(kb0 + (size_t)(kbs - 2) * 64 * LDP_O, LDP_O); pfv = tile_fetch(vb0 + (kbs - 2) * 64, SEQ);
;     pfk1 = tile_fetch(kb0 + (size_t)(kbs - 3) * 64 * LDP_O, LDP_O); pfv1 = tile_fetch(vb0 + (kbs - 3) * 64, SEQ);
;   }
.LBB0_483:
	s_and_b32 s0, s7, 15
	s_lshl_b32 s1, s0, 2
	s_ashr_i32 s12, s8, 4
	s_add_i32 s9, s1, 5
	v_mov_b32_e32 v20, v167
	s_ashr_i32 s14, s8, 8
	s_lshl_b32 s1, s12, 6
	s_lshl_b32 s0, s0, 8
	s_ashr_i32 s15, s14, 31
	v_ashrrev_i32_e32 v0, 1, v20
	s_and_b32 s11, s1, 0x3c0
	s_or_b32 s10, s0, 0xff
	s_and_b32 s0, s8, 15
	v_and_b32_e32 v0, 0xffffffe0, v0
	s_lshl_b64 s[16:17], s[14:15], 12
	s_lshl_b32 s28, s11, 1
	s_lshl_b64 s[14:15], s[14:15], 24
	v_and_b32_e32 v21, 31, v20
	v_lshl_add_u32 v118, s0, 8, v0
	s_add_u32 s1, s60, s14
	v_or_b32_e32 v112, v118, v21
	s_addc_u32 s13, s61, s15
	v_ashrrev_i32_e32 v113, 31, v112
	s_add_u32 s44, s1, s28
	v_lshl_add_u64 v[114:115], s[16:17], 0, v[112:113]
	s_addc_u32 s45, s13, 0
	s_ashr_i32 s13, s12, 31
	v_lshlrev_b64 v[2:3], 12, v[114:115]
	s_lshl_b64 s[12:13], s[12:13], 19
	v_bfe_u32 v22, v20, 5, 1
	v_lshl_add_u64 v[2:3], s[60:61], 0, v[2:3]
	s_add_u32 s46, s82, s12
	v_lshl_add_u64 v[2:3], v[2:3], 0, s[28:29]
	v_lshlrev_b32_e32 v0, 4, v22
	s_addc_u32 s47, s83, s13
	s_lshl_b32 s1, s0, 2
	v_lshl_add_u64 v[2:3], v[2:3], 0, v[0:1]
	s_or_b32 s14, s1, 3
	v_mov_b32_e32 v0, v167
	global_load_dwordx4 v[80:83], v[2:3], off
	global_load_dwordx4 v[84:87], v[2:3], off offset:32
	global_load_dwordx4 v[88:91], v[2:3], off offset:64
	global_load_dwordx4 v[92:95], v[2:3], off offset:96
	s_lshl_b32 s12, s14, 18
	s_add_u32 s12, s44, s12
	v_ashrrev_i32_e32 v2, 3, v0
	v_ashrrev_i32_e32 v3, 31, v2
	s_addc_u32 s13, s45, 0
	v_lshlrev_b64 v[2:3], 12, v[2:3]
	v_lshlrev_b32_e32 v0, 4, v0
	v_lshl_add_u64 v[2:3], s[12:13], 0, v[2:3]
	v_and_b32_e32 v0, 0x70, v0
	v_lshl_add_u64 v[2:3], v[2:3], 0, v[0:1]
	v_mov_b32_e32 v0, v167
	global_load_dwordx4 v[2:5], v[2:3], off offset:2048
	s_lshl_b32 s12, s14, 7
	s_add_u32 s12, s46, s12
	v_ashrrev_i32_e32 v6, 3, v0
	v_ashrrev_i32_e32 v7, 31, v6
	s_addc_u32 s13, s47, 0
	v_lshlrev_b64 v[6:7], 13, v[6:7]
	v_lshlrev_b32_e32 v0, 4, v0
	v_lshl_add_u64 v[6:7], s[12:13], 0, v[6:7]
	v_and_b32_e32 v0, 0x70, v0
	v_lshl_add_u64 v[6:7], v[6:7], 0, v[0:1]
	s_or_b32 s14, s1, 2
	v_mov_b32_e32 v0, v167
	s_waitcnt lgkmcnt(0)
	global_load_dwordx4 v[6:9], v[6:7], off
	s_lshl_b32 s12, s14, 18
	s_add_u32 s12, s44, s12
	v_ashrrev_i32_e32 v10, 3, v0
	v_ashrrev_i32_e32 v11, 31, v10
	s_addc_u32 s13, s45, 0
	v_lshlrev_b64 v[10:11], 12, v[10:11]
	v_lshlrev_b32_e32 v0, 4, v0
	v_lshl_add_u64 v[10:11], s[12:13], 0, v[10:11]
	v_and_b32_e32 v0, 0x70, v0
	v_lshl_add_u64 v[10:11], v[10:11], 0, v[0:1]
	v_mov_b32_e32 v0, v167
	global_load_dwordx4 v[10:13], v[10:11], off offset:2048
	s_lshl_b32 s12, s14, 7
	s_add_u32 s12, s46, s12
	v_ashrrev_i32_e32 v14, 3, v0
	v_ashrrev_i32_e32 v15, 31, v14
	s_addc_u32 s13, s47, 0
	v_lshlrev_b64 v[14:15], 13, v[14:15]
	v_lshlrev_b32_e32 v0, 4, v0
	v_lshl_add_u64 v[14:15], s[12:13], 0, v[14:15]
	v_and_b32_e32 v0, 0x70, v0
	v_lshl_add_u64 v[14:15], v[14:15], 0, v[0:1]
	global_load_dwordx4 v[14:17], v[14:15], off
	v_lshrrev_b32_e32 v226, 3, v167
	v_and_b32_e32 v228, 7, v167
	v_lshlrev_b32_e32 v228, 4, v228
	v_lshl_add_u32 v230, v226, 12, v228
	v_lshl_add_u32 v228, v226, 13, v228
	v_mov_b32_e32 v231, 0
	v_mov_b32_e32 v229, 0
	s_or_b32 s12, s1, 1
	s_lshl_b32 s12, s12, 18
	s_add_u32 s12, s44, s12
	s_addc_u32 s13, s45, 0
	v_lshl_add_u64 v[224:225], s[12:13], 0, v[230:231]
	global_load_dwordx4 v[96:99], v[224:225], off offset:2048
	s_or_b32 s12, s1, 1
	s_lshl_b32 s12, s12, 7
	s_add_u32 s12, s46, s12
	s_addc_u32 s13, s47, 0
	v_lshl_add_u64 v[224:225], s[12:13], 0, v[228:229]
	global_load_dwordx4 v[100:103], v[224:225], off
	s_lshl_b32 s12, s0, 20
	s_add_u32 s12, s44, s12
	s_addc_u32 s13, s45, 0
	v_lshl_add_u64 v[224:225], s[12:13], 0, v[230:231]
	global_load_dwordx4 v[104:107], v[224:225], off offset:2048
	s_lshl_b32 s12, s0, 9
	s_add_u32 s12, s46, s12
	s_addc_u32 s13, s47, 0
	v_lshl_add_u64 v[224:225], s[12:13], 0, v[228:229]
	global_load_dwordx4 v[108:111], v[224:225], off
	v_mov_b32_e32 v0, v167
	s_waitcnt vmcnt(0)
	s_barrier
; DI void sb_item(const bf16_t* __restrict__ P, const bf16_t* __restrict__ VT, bf16_t* __restrict__ Y, int item, char* lds) {
;     ...
;   f32x16 O[2], S[2];
; #pragma unroll
;   for (int dt = 0; dt < 2; ++dt)
; #pragma unroll
;     for (int e = 0; e < 16; ++e) O[dt][e] = 0.f;
;   float carry = 1.f;
;   const bf16_t* kb0 = P + tokbase * LDP_O + 1024 + hd * 64;
;   const bf16_t* vb0 = VT + (size_t)bh * 64 * SEQ;
;   const int kbs = 4 * qb + 3;
;   constexpr int TS = 64 * LDT;
;   u32x4 pfk = tile_fetch(kb0 + (size_t)kbs * 64 * LDP_O, LDP_O), pfv = tile_fetch(vb0 + kbs * 64, SEQ);
;   u32x4 pfk1 = tile_fetch(kb0 + (size_t)(kbs - 1) * 64 * LDP_O, LDP_O), pfv1 = tile_fetch(vb0 + (kbs - 1) * 64, SEQ);
;   __syncthreads();
;   tile_commit(Ks, pfk); tile_commit(Ks + TS, pfv); tile_commit(Ks + 2 * TS, pfk1); tile_commit(Ks + 3 * TS, pfv1);
;   if (kbs >= 3) {
;     pfk = tile_fetch(kb0 + (size_t)(kbs - 2) * 64 * LDP_O, LDP_O); pfv = tile_fetch(vb0 + (kbs - 2) * 64, SEQ);
;     pfk1 = tile_fetch(kb0 + (size_t)(kbs - 3) * 64 * LDP_O, LDP_O); pfv1 = tile_fetch(vb0 + (kbs - 3) * 64, SEQ);
;   }
;   __syncthreads();
;   int par = 0, fi = 0;
	s_or_b32 s1, s1, 1
	v_lshrrev_b32_e32 v18, 3, v0
	v_lshlrev_b32_e32 v0, 4, v0
	v_and_b32_e32 v0, 0x70, v0
	v_mad_u64_u32 v[18:19], s[12:13], v18, s92, v[0:1]
	v_mov_b32_e32 v0, v167
	v_mul_u32_u24_e32 v120, 0x48, v21
	v_lshl_add_u32 v121, v22, 3, v120
	v_lshlrev_b32_e32 v113, 2, v22
	v_cmp_eq_u32_e64 s[40:41], 0, v22
	v_cmp_eq_u32_e64 s[42:43], 0, v20
	v_or_b32_e32 v119, 31, v118
	v_mov_b32_e32 v117, 1.0
	s_mov_b64 s[34:35], 0
	ds_write_b128 v18, v[2:5]
	v_mov_b32_e32 v4, v1
	v_lshrrev_b32_e32 v2, 3, v0
	v_lshlrev_b32_e32 v0, 4, v0
	v_and_b32_e32 v0, 0x70, v0
	v_mad_u64_u32 v[2:3], s[12:13], v2, s92, v[0:1]
	v_mov_b32_e32 v0, v167
	v_mov_b32_e32 v5, v1
	ds_write_b128 v2, v[6:9] offset:9216
	v_mov_b32_e32 v6, v1
	v_lshrrev_b32_e32 v2, 3, v0
	v_lshlrev_b32_e32 v0, 4, v0
	v_and_b32_e32 v0, 0x70, v0
	v_mad_u64_u32 v[2:3], s[12:13], v2, s92, v[0:1]
	v_mov_b32_e32 v0, v167
	v_mov_b32_e32 v7, v1
	v_mov_b32_e32 v8, v1
	v_mov_b32_e32 v9, v1
	ds_write_b128 v2, v[10:13] offset:18432
	v_mov_b32_e32 v10, v1
	v_lshrrev_b32_e32 v2, 3, v0
	v_lshlrev_b32_e32 v0, 4, v0
	v_and_b32_e32 v0, 0x70, v0
	v_mad_u64_u32 v[2:3], s[12:13], v2, s92, v[0:1]
	v_mov_b32_e32 v0, v167
	s_lshl_b32 s12, s1, 18
	s_add_u32 s12, s44, s12
	s_addc_u32 s13, s45, 0
	ds_write_b128 v2, v[14:17] offset:27648
	s_lshl_b32 s1, s1, 7
	v_ashrrev_i32_e32 v2, 3, v0
	v_ashrrev_i32_e32 v3, 31, v2
	v_lshlrev_b64 v[2:3], 12, v[2:3]
	v_lshlrev_b32_e32 v0, 4, v0
	v_lshl_add_u64 v[2:3], s[12:13], 0, v[2:3]
	v_and_b32_e32 v0, 0x70, v0
	v_lshl_add_u64 v[2:3], v[2:3], 0, v[0:1]
	v_mov_b32_e32 v0, v167
	s_nop 0
	s_add_u32 s12, s46, s1
	v_ashrrev_i32_e32 v2, 3, v0
	v_ashrrev_i32_e32 v3, 31, v2
	s_addc_u32 s13, s47, 0
	v_lshlrev_b64 v[2:3], 13, v[2:3]
	v_lshlrev_b32_e32 v0, 4, v0
	v_lshl_add_u64 v[2:3], s[12:13], 0, v[2:3]
	v_and_b32_e32 v0, 0x70, v0
	v_lshl_add_u64 v[2:3], v[2:3], 0, v[0:1]
	v_mov_b32_e32 v0, v167
	s_nop 0
	s_lshl_b32 s1, s0, 20
	s_add_u32 s12, s44, s1
	v_ashrrev_i32_e32 v2, 3, v0
	v_ashrrev_i32_e32 v3, 31, v2
	s_addc_u32 s13, s45, 0
	v_lshlrev_b64 v[2:3], 12, v[2:3]
	v_lshlrev_b32_e32 v0, 4, v0
	v_lshl_add_u64 v[2:3], s[12:13], 0, v[2:3]
	v_and_b32_e32 v0, 0x70, v0
	v_lshl_add_u64 v[2:3], v[2:3], 0, v[0:1]
	v_mov_b32_e32 v0, v167
	s_nop 0
	s_lshl_b32 s0, s0, 9
	s_add_u32 s0, s46, s0
	v_ashrrev_i32_e32 v2, 3, v0
	v_ashrrev_i32_e32 v3, 31, v2
	s_addc_u32 s1, s47, 0
	v_lshlrev_b64 v[2:3], 13, v[2:3]
	v_lshlrev_b32_e32 v0, 4, v0
	v_lshl_add_u64 v[2:3], s[0:1], 0, v[2:3]
	v_and_b32_e32 v0, 0x70, v0
	v_lshl_add_u64 v[2:3], v[2:3], 0, v[0:1]
	s_nop 0
	v_mov_b32_e32 v14, v1
	v_mov_b32_e32 v15, v1
	v_mov_b32_e32 v0, v1
	v_mov_b32_e32 v2, v1
	v_mov_b32_e32 v3, v1
	v_mov_b32_e32 v11, v1
	v_mov_b32_e32 v12, v1
	v_mov_b32_e32 v13, v1
	v_mov_b64_e32 v[30:31], v[14:15]
	v_mov_b64_e32 v[46:47], v[14:15]
	s_mov_b32 s12, 0
	v_mov_b64_e32 v[28:29], v[12:13]
	v_mov_b64_e32 v[26:27], v[10:11]
	v_mov_b64_e32 v[24:25], v[8:9]
	v_mov_b64_e32 v[22:23], v[6:7]
	v_mov_b64_e32 v[20:21], v[4:5]
	v_mov_b64_e32 v[18:19], v[2:3]
	v_mov_b64_e32 v[16:17], v[0:1]
	v_mov_b64_e32 v[44:45], v[12:13]
	v_mov_b64_e32 v[42:43], v[10:11]
	v_mov_b64_e32 v[40:41], v[8:9]
	v_mov_b64_e32 v[38:39], v[6:7]
	v_mov_b64_e32 v[36:37], v[4:5]
	v_mov_b64_e32 v[34:35], v[2:3]
	v_mov_b64_e32 v[32:33], v[0:1]
	s_mov_b32 s13, 0
	s_waitcnt lgkmcnt(0)
	s_barrier
	s_branch .LBB0_485
